# static priority raise for waves 4-7 also in the chunked RWKV (R4) unit loop
# baseline (speedup 1.0000x reference)
.LBB0_508:
	s_andn2_b64 vcc, exec, s[0:1]
	s_cbranch_vccnz .LBB0_544
	v_readlane_b32 s4, v251, 0
	s_mov_b64 s[0:1], 0
	v_mov_b32_e32 v2, v202
	s_mov_b32 s34, s4
	s_cmpk_gt_i32 s34, 0xfff
	s_cbranch_scc1 .LBB0_544
	s_add_u32 s4, s26, s0
	s_addc_u32 s5, s27, s1
	s_add_u32 s52, s4, 0x1b000000
	s_addc_u32 s53, s5, 0
	s_lshl_b32 s0, s34, 2
	s_waitcnt vmcnt(0)
	v_lshrrev_b32_e32 v0, 3, v2
	v_mov_b32_e32 v10, s0
	s_movk_i32 s0, 0xffc0
	v_bfi_b32 v10, s0, v10, v0
	v_ashrrev_i32_e32 v18, 6, v2
	v_ashrrev_i32_e32 v11, 31, v10
	v_lshlrev_b32_e32 v14, 3, v2
	v_lshlrev_b64 v[10:11], 11, v[10:11]
	s_lshl_b32 s0, s34, 7
	v_lshlrev_b32_e32 v122, 10, v18
	v_and_b32_e32 v8, 56, v14
	v_lshl_add_u64 v[10:11], s[52:53], 0, v[10:11]
	s_and_b32 s72, s0, 0x780
	v_add_u32_e32 v123, 0, v122
	v_lshl_add_u64 v[10:11], v[10:11], 0, s[72:73]
	v_lshlrev_b32_e32 v0, 1, v8
	v_readfirstlane_b32 s0, v123
	v_lshl_add_u64 v[10:11], v[10:11], 0, v[0:1]
	s_mov_b32 m0, s0
	s_mov_b64 s[0:1], 0x2000000
	v_add_u32_e32 v124, 0x2000, v123
	v_lshl_add_u64 v[12:13], v[10:11], 0, s[0:1]
	v_readfirstlane_b32 s0, v124
	global_load_lds_dwordx4 v[10:11], off
	s_mov_b32 m0, s0
	s_mov_b64 s[0:1], 0x4000000
	v_add_u32_e32 v125, 0x4000, v123
	global_load_lds_dwordx4 v[12:13], off
	v_lshl_add_u64 v[12:13], v[10:11], 0, s[0:1]
	v_readfirstlane_b32 s0, v125
	s_mov_b32 m0, s0
	s_mov_b64 s[0:1], 0x6000000
	v_add_u32_e32 v126, 0x6000, v123
	global_load_lds_dwordx4 v[12:13], off
	v_lshl_add_u64 v[12:13], v[10:11], 0, s[0:1]
	v_readfirstlane_b32 s0, v126
	s_mov_b32 m0, s0
	s_mov_b64 s[0:1], 0x8000000
	v_add_u32_e32 v127, 0x8000, v123
	global_load_lds_dwordx4 v[12:13], off
	v_lshl_add_u64 v[12:13], v[10:11], 0, s[0:1]
	v_readfirstlane_b32 s0, v127
	s_lshl_b32 s54, s78, 1
	s_mov_b32 s55, s73
	s_mov_b32 m0, s0
	v_lshl_add_u64 v[10:11], v[10:11], 0, s[54:55]
	s_mov_b64 s[0:1], 0xa000000
	v_add_u32_e32 v128, 0xa000, v123
	v_lshl_add_u64 v[10:11], v[10:11], 0, s[0:1]
	v_readfirstlane_b32 s0, v128
	global_load_lds_dwordx4 v[12:13], off
	s_mov_b32 m0, s0
	s_waitcnt lgkmcnt(0)
	v_and_b32_e32 v3, 63, v2
	global_load_lds_dwordx4 v[10:11], off
	v_lshlrev_b32_e32 v10, 1, v3
	v_cmp_eq_u32_e64 s[0:1], 7, v18
	v_and_b32_e32 v9, 15, v2
	v_add_u32_e32 v129, 0, v10
	v_writelane_b32 v254, s0, 12
	v_ashrrev_i32_e32 v19, 7, v2
	v_add_u32_e32 v131, v129, v10
	v_writelane_b32 v254, s1, 13
	v_mul_u32_u24_e32 v10, 0x10c, v3
	v_lshlrev_b32_e32 v11, 5, v18
	v_lshl_or_b32 v20, v19, 4, v9
	s_movk_i32 s0, 0x90
	v_add3_u32 v132, v131, v10, v11
	v_mul_u32_u24_e32 v10, 0x48, v3
	v_mul_lo_u32 v16, v20, s0
	v_lshlrev_b32_e32 v11, 1, v10
	v_add_u32_e32 v10, 0, v16
	v_lshlrev_b32_e32 v12, 1, v18
	s_movk_i32 s0, 0x70
	v_and_b32_e32 v21, 2, v12
	v_mad_u64_u32 v[12:13], s[0:1], v20, s0, v[10:11]
	v_readlane_b32 s0, v252, 50
	v_ashrrev_i32_e32 v24, 3, v2
	v_bfe_u32 v14, v14, 4, 2
	v_add_u32_e32 v13, s0, v16
	v_readlane_b32 s0, v252, 51
	v_cmp_lt_i32_e64 s[42:43], v14, v19
	s_add_u32 s47, s4, 0xe000000
	v_add_u32_e32 v23, s0, v16
	s_movk_i32 s0, 0xff90
	v_mul_lo_u32 v14, v24, s0
	v_readlane_b32 s0, v252, 49
	s_addc_u32 s55, s5, 0
	s_add_u32 s72, s4, 0x10000000
	v_add_u32_e32 v138, s0, v16
	s_movk_i32 s0, 0x80
	v_cmp_gt_i32_e64 s[44:45], s0, v2
	v_readlane_b32 s0, v252, 52
	v_lshlrev_b32_e32 v15, 4, v18
	v_readlane_b32 s6, v252, 47
	v_mov_b32_e32 v26, s0
	s_addc_u32 s0, s5, 0
	v_lshl_add_u32 v25, v24, 8, 0
	v_and_b32_e32 v139, 48, v2
	v_writelane_b32 v254, s0, 14
	s_add_u32 s0, s4, 0x14000000
	v_add3_u32 v135, s6, v11, v15
	v_add3_u32 v137, v25, v14, v0
	v_add_u32_e32 v0, s6, v139
	v_readlane_b32 s6, v252, 53
	v_writelane_b32 v254, s0, 16
	s_addc_u32 s0, s5, 0
	v_mov_b32_e32 v14, s6
	v_cmp_gt_i32_e32 vcc, 4, v18
	v_writelane_b32 v254, s0, 18
	s_add_u32 s0, s4, 0x16000000
	v_cndmask_b32_e32 v27, v14, v26, vcc
	v_cmp_gt_i32_e32 vcc, 64, v2
	v_writelane_b32 v254, s0, 20
	s_addc_u32 s0, s5, 0
	v_readlane_b32 s35, v252, 45
	v_readlane_b32 s37, v252, 46
	v_cndmask_b32_e32 v14, v14, v26, vcc
	v_writelane_b32 v254, s0, 22
	s_movk_i32 s0, 0x240
	v_add3_u32 v133, s35, v11, v15
	v_add3_u32 v134, s37, v11, v15
	s_movk_i32 s7, 0x110
	v_add_u32_e32 v140, v14, v11
	v_mul_lo_u32 v11, v18, s0
	v_lshl_add_u32 v130, v2, 2, 0
	v_lshrrev_b32_e32 v17, 2, v2
	v_mul_lo_u32 v29, v2, s7
	v_and_b32_e32 v30, 0xffffff80, v2
	v_lshl_or_b32 v2, v18, 3, 1
	v_or_b32_e32 v11, v11, v3
	s_movk_i32 s0, 0x48
	v_readlane_b32 s1, v252, 48
	v_lshlrev_b32_e32 v32, 7, v2
	v_lshlrev_b32_e32 v11, 1, v11
	v_mul_lo_u32 v2, v2, s0
	v_add_u32_e32 v143, 0, v11
	v_add_u32_e32 v144, s6, v11
	v_add_u32_e32 v145, s1, v11
	v_add_lshl_u32 v11, v2, v3, 1
	v_add_u32_e32 v147, s6, v11
	v_add_u32_e32 v148, s1, v11
	v_add_u32_e32 v11, 0x48, v2
	v_lshl_add_u32 v149, v11, 1, v129
	v_add_lshl_u32 v11, v11, v3, 1
	v_add_u32_e32 v150, s6, v11
	v_add_u32_e32 v151, s1, v11
	v_add_u32_e32 v11, 0x90, v2
	v_cmp_lt_i32_e64 s[4:5], 0, v18
	v_lshl_add_u32 v164, v11, 1, v129
	v_add_lshl_u32 v11, v11, v3, 1
	v_writelane_b32 v254, s4, 24
	v_add_u32_e32 v165, s6, v11
	v_add_u32_e32 v166, s1, v11
	v_add_u32_e32 v11, 0xd8, v2
	v_writelane_b32 v254, s5, 25
	v_cmp_lt_i32_e64 s[4:5], 1, v18
	v_lshl_add_u32 v167, v11, 1, v129
	v_add_lshl_u32 v11, v11, v3, 1
	v_writelane_b32 v254, s4, 26
	v_add_u32_e32 v168, s6, v11
	v_add_u32_e32 v169, s1, v11
	v_add_u32_e32 v11, 0x120, v2
	v_writelane_b32 v254, s5, 27
	v_cmp_lt_i32_e64 s[4:5], 2, v18
	v_lshl_add_u32 v170, v11, 1, v129
	v_add_lshl_u32 v11, v11, v3, 1
	v_writelane_b32 v254, s4, 28
	v_lshl_add_u32 v146, v2, 1, v129
	v_add_u32_e32 v171, s6, v11
	v_add_u32_e32 v172, s1, v11
	v_add_u32_e32 v11, 0x168, v2
	v_add_u32_e32 v2, 0x1b0, v2
	v_and_or_b32 v28, v15, 48, v9
	v_writelane_b32 v254, s5, 29
	v_cmp_lt_i32_e64 s[4:5], 3, v18
	v_lshl_add_u32 v176, v2, 1, v129
	v_add_lshl_u32 v2, v2, v3, 1
	v_and_b32_e32 v22, 12, v17
	v_mul_u32_u24_e32 v28, 0x90, v28
	v_writelane_b32 v254, s4, 30
	v_add_u32_e32 v177, s6, v2
	v_add_u32_e32 v178, s1, v2
	v_lshlrev_b32_e32 v2, 4, v21
	v_and_b32_e32 v31, 4, v17
	v_writelane_b32 v254, s5, 31
	v_cmp_lt_i32_e64 s[4:5], 4, v18
	v_or_b32_e32 v17, 1, v21
	v_add3_u32 v185, v27, v28, v139
	v_or_b32_e32 v28, v2, v22
	v_add_u32_e32 v26, s1, v16
	v_writelane_b32 v254, s4, 32
	v_add_u32_e32 v179, v10, v139
	v_or_b32_e32 v10, v2, v9
	v_lshlrev_b32_e32 v39, 4, v17
	v_lshlrev_b32_e32 v2, 1, v28
	v_writelane_b32 v254, s5, 33
	v_cmp_lt_i32_e64 s[4:5], 5, v18
	v_lshl_add_u32 v173, v11, 1, v129
	v_add_lshl_u32 v11, v11, v3, 1
	v_or_b32_e32 v40, v39, v9
	v_lshlrev_b32_e32 v3, 2, v3
	v_add_u32_e32 v197, v138, v2
	v_add_u32_e32 v198, v13, v2
	v_add_u32_e32 v199, v23, v2
	v_add_u32_e32 v201, v26, v2
	v_and_b32_e32 v2, 0x50, v2
	v_writelane_b32 v254, s4, 34
	v_add_u32_e32 v175, s1, v11
	v_mul_u32_u24_e32 v14, 0x48, v40
	v_add3_u32 v190, s35, v16, v139
	v_add3_u32 v191, s6, v16, v139
	v_add_u32_e32 v192, v0, v16
	v_lshl_or_b32 v16, v19, 10, v3
	v_or_b32_e32 v3, 1, v28
	v_or3_b32 v2, v30, v2, v9
	v_cmp_eq_u32_e64 s[0:1], v28, v20
	v_writelane_b32 v254, s5, 35
	v_cmp_lt_i32_e64 s[4:5], 6, v18
	v_lshlrev_b32_e32 v41, 1, v14
	v_lshl_or_b32 v14, v2, 3, v31
	v_cndmask_b32_e64 v2, 0, 1.0, s[0:1]
	v_cmp_eq_u32_e64 s[0:1], v3, v20
	v_or_b32_e32 v45, 3, v28
	v_or_b32_e32 v46, 2, v28
	v_or_b32_e32 v15, v22, v15
	v_writelane_b32 v254, s4, 36
	v_cmp_lt_i32_e32 vcc, v3, v20
	v_cndmask_b32_e64 v3, 0, 1.0, s[0:1]
	v_cmp_lt_i32_e64 s[0:1], v46, v20
	v_cmp_lt_i32_e64 s[10:11], v45, v20
	v_or_b32_e32 v22, v39, v22
	v_writelane_b32 v254, s5, 37
	v_add_u32_e32 v174, s6, v11
	v_mul_u32_u24_e32 v11, 0x48, v10
	v_lshl_add_u32 v196, v28, 2, v12
	v_lshl_add_u32 v216, v22, 2, v12
	v_lshlrev_b32_e32 v12, 1, v22
	s_or_b64 s[64:65], s[10:11], s[0:1]
	v_cmp_lt_i32_e64 s[0:1], 7, v18
	v_and_b32_e32 v141, 63, v24
	v_lshlrev_b32_e32 v24, 2, v20
	v_lshlrev_b32_e32 v11, 1, v11
	v_add_u32_e32 v189, v23, v139
	v_mad_u32_u24 v43, v28, s7, 0
	v_add_u32_e32 v219, v23, v12
	v_mad_u32_u24 v23, v22, s7, 0
	v_writelane_b32 v254, s0, 38
	v_add_u32_e32 v142, 0, v24
	v_add3_u32 v182, s6, v11, v139
	v_add3_u32 v184, s6, v41, v139
	v_mul_lo_u32 v27, v15, s7
	v_add_u32_e32 v200, v43, v24
	v_or_b32_e32 v39, 1, v22
	v_add_u32_e32 v217, v138, v12
	v_add_u32_e32 v218, v13, v12
	v_add_u32_e32 v220, v23, v24
	v_add_u32_e32 v221, v26, v12
	v_and_b32_e32 v12, 0x70, v12
	v_cmp_eq_u32_e64 s[6:7], v22, v20
	v_or_b32_e32 v24, 3, v22
	v_writelane_b32 v254, s1, 39
	v_cmp_le_i32_e64 s[0:1], v21, v19
	v_lshl_add_u32 v136, v8, 2, v25
	v_lshl_add_u32 v25, v9, 2, 0
	v_add_u32_e32 v180, v26, v139
	v_mul_u32_u24_e32 v42, 0x90, v10
	v_mul_u32_u24_e32 v10, 0x90, v9
	v_cmp_eq_u32_e64 s[4:5], v45, v20
	v_or3_b32 v9, v30, v12, v9
	v_cndmask_b32_e64 v106, 0, 1.0, s[6:7]
	v_cmp_eq_u32_e64 s[6:7], v39, v20
	v_or_b32_e32 v26, 2, v22
	v_cmp_eq_u32_e64 s[8:9], v24, v20
	v_writelane_b32 v254, s0, 40
	v_add3_u32 v186, 0, v10, v139
	v_lshl_or_b32 v10, v21, 8, v16
	v_cndmask_b32_e64 v105, 0, 1.0, s[4:5]
	v_cmp_eq_u32_e64 s[4:5], v46, v20
	v_lshl_or_b32 v16, v17, 8, v16
	v_lshl_or_b32 v12, v9, 3, v31
	v_cndmask_b32_e64 v107, 0, 1.0, s[6:7]
	v_cmp_lt_i32_e64 s[6:7], v26, v20
	v_cmp_lt_i32_e64 s[96:97], v24, v20
	v_cndmask_b32_e64 v109, 0, 1.0, s[8:9]
	v_cmp_eq_u32_e64 s[8:9], v26, v20
	v_writelane_b32 v254, s1, 41
	v_cmp_lt_i32_e64 s[0:1], v21, v19
	v_or_b32_e32 v33, 0x100, v122
	v_or_b32_e32 v34, 0x180, v122
	v_or_b32_e32 v35, 0x200, v122
	v_or_b32_e32 v36, 0x280, v122
	v_or_b32_e32 v37, 0x300, v122
	v_or_b32_e32 v38, 0x380, v122
	v_add3_u32 v181, 0, v11, v139
	v_add_u32_e32 v188, v13, v139
	v_add_u32_e32 v193, v0, v11
	v_add3_u32 v194, s35, v11, v139
	v_add3_u32 v195, s37, v11, v139
	v_ashrrev_i32_e32 v11, 31, v10
	v_ashrrev_i32_e32 v15, 31, v14
	v_mul_i32_i24_e32 v44, 0xfffffef4, v28
	v_cndmask_b32_e64 v104, 0, 1.0, s[4:5]
	v_ashrrev_i32_e32 v17, 31, v16
	v_cmp_lt_i32_e64 s[4:5], v39, v20
	v_ashrrev_i32_e32 v13, 31, v12
	v_mul_i32_i24_e32 v9, 0xfffffef4, v22
	v_cndmask_b32_e64 v108, 0, 1.0, s[8:9]
	v_mul_u32_u24_e32 v30, 0x90, v40
	s_add_i32 s8, s28, s34
	s_or_b64 s[68:69], s[96:97], s[6:7]
	v_writelane_b32 v254, s0, 42
	v_add3_u32 v183, 0, v41, v139
	v_add_u32_e32 v187, 0xf500, v186
	v_lshl_add_u32 v215, v46, 2, 0
	v_lshl_add_u32 v222, v26, 2, 0
	v_add_u32_e32 v223, v0, v41
	v_add3_u32 v224, s35, v41, v139
	v_add3_u32 v225, s37, v41, v139
	s_lshl_b32 s37, s8, 2
	s_lshl_b32 s38, s8, 6
	v_add_u32_e32 v226, v129, v32
	v_add_u32_e32 v227, v129, v33
	v_add_u32_e32 v228, v129, v34
	v_add_u32_e32 v229, v129, v35
	v_add_u32_e32 v230, v129, v36
	v_add_u32_e32 v231, v129, v37
	v_add_u32_e32 v232, v129, v38
	v_add_u32_e32 v233, v0, v42
	v_add_u32_e32 v234, v0, v30
	v_lshlrev_b32_e32 v0, 1, v8
	v_lshlrev_b64 v[110:111], 1, v[14:15]
	v_lshlrev_b64 v[112:113], 1, v[10:11]
	v_add_u32_e32 v235, v43, v44
	v_lshlrev_b64 v[114:115], 1, v[12:13]
	v_lshlrev_b64 v[116:117], 1, v[16:17]
	v_add_u32_e32 v236, v23, v9
	s_or_b64 s[66:67], s[64:65], vcc
	s_or_b64 s[70:71], s[68:69], s[4:5]
	v_add_u32_e32 v237, 0, v29
	v_add_u32_e32 v238, v25, v27
	s_lshl_b32 s39, s34, 8
	v_writelane_b32 v254, s1, 43
	v_cmp_lt_i32_e64 s[78:79], v28, v20
	v_cmp_gt_i32_e64 s[6:7], v28, v20
	v_cmp_gt_i32_e64 s[82:83], v46, v20
	v_cmp_gt_i32_e64 s[84:85], v45, v20
	v_cmp_lt_i32_e64 s[86:87], v22, v20
	v_cmp_gt_i32_e64 s[88:89], v22, v20
	v_cmp_gt_i32_e64 s[90:91], v26, v20
	v_cmp_gt_i32_e64 s[92:93], v24, v20
	v_readfirstlane_b32 s100, v202
	s_nop 3
	s_lshr_b32 s100, s100, 6
	s_cmp_ge_u32 s100, 4
	s_cbranch_scc0 .Lr4_prio_done
	s_setprio 1
.Lr4_prio_done:
	s_branch .LBB0_512
.LBB0_511:
	ds_read_b128 v[8:11], v181 offset:53504
	ds_read_b128 v[32:35], v188
	ds_read_b128 v[12:15], v182
	ds_read_b128 v[16:19], v193
	ds_read_b128 v[36:39], v189
	ds_read_b128 v[58:61], v190
	ds_read_b128 v[24:27], v194
	s_waitcnt lgkmcnt(0)
	v_mfma_f32_16x16x32_bf16 v[20:23], v[8:11], v[32:35], 0
	s_ashr_i32 s35, s34, 31
	s_ashr_i32 s41, s34, 4
	s_lshl_b64 s[4:5], s[34:35], 13
	v_mfma_f32_16x16x32_bf16 v[12:15], v[12:15], v[32:35], 0
	s_add_u32 s0, s47, s4
	s_addc_u32 s1, s55, s5
	s_and_b32 s34, s39, 0xf00
	v_mfma_f32_16x16x32_bf16 v[12:15], v[16:19], v[36:39], v[12:15]
	ds_read_b128 v[62:65], v191
	ds_read_b128 v[16:19], v195
	ds_read_b128 v[52:55], v192
	ds_read_b128 v[40:43], v181 offset:53568
	s_add_i32 s34, s34, s41
	v_mfma_f32_16x16x32_bf16 v[28:31], v[8:11], v[58:61], 0
	s_ashr_i32 s35, s34, 31
	v_lshl_add_u64 v[84:85], s[0:1], 0, v[110:111]
	s_lshl_b64 vcc, s[34:35], 13
	s_waitcnt lgkmcnt(0)
	v_mfma_f32_16x16x32_bf16 v[8:11], v[24:27], v[62:65], 0
	ds_read_b128 v[24:27], v188 offset:64
	ds_read_b128 v[44:47], v182 offset:64
	v_readlane_b32 s34, v254, 16
	s_add_u32 s34, s34, vcc_lo
	v_mfma_f32_16x16x32_bf16 v[48:51], v[16:19], v[52:55], v[8:11]
	v_readlane_b32 s35, v254, 18
	s_addc_u32 s35, s35, vcc_hi
	s_add_u32 s4, s72, s4
	ds_read_b128 v[8:11], v193 offset:64
	s_waitcnt lgkmcnt(0)
	v_mfma_f32_16x16x32_bf16 v[66:69], v[40:43], v[24:27], v[20:23]
	v_readlane_b32 s41, v254, 14
	s_addc_u32 s5, s41, s5
	v_readlane_b32 s41, v254, 20
	ds_read_b128 v[20:23], v189 offset:64
	v_mfma_f32_16x16x32_bf16 v[44:47], v[44:47], v[24:27], v[12:15]
	ds_read_b128 v[16:19], v190 offset:64
	s_nop 1
	ds_read_b128 v[12:15], v191 offset:64
	ds_read_b128 v[70:73], v194 offset:64
	s_add_u32 vcc_lo, s41, vcc_lo
	v_readlane_b32 s41, v254, 22
	s_waitcnt lgkmcnt(0)
	v_mfma_f32_16x16x32_bf16 v[74:77], v[8:11], v[20:23], v[44:47]
	ds_read_b128 v[8:11], v192 offset:64
	s_addc_u32 vcc_hi, s41, vcc_hi
	s_add_i32 s39, s39, s29
	ds_read_b128 v[44:47], v195 offset:64
	v_mfma_f32_16x16x32_bf16 v[28:31], v[40:43], v[16:19], v[28:31]
	s_add_i32 s37, s37, s94
	s_add_i32 s38, s38, s80
	v_mfma_f32_16x16x32_bf16 v[40:43], v[70:73], v[12:15], v[48:51]
	ds_read_b64 v[82:83], v201
	ds_read_b32 v56, v142 offset:51200
	ds_read_b128 v[70:73], v183 offset:53504
	ds_read_b128 v[48:51], v184
	ds_read_b128 v[78:81], v223
	s_waitcnt lgkmcnt(0)
	v_mfma_f32_16x16x32_bf16 v[40:43], v[44:47], v[8:11], v[40:43]
	v_lshlrev_b32_e32 v44, 16, v82
	v_and_b32_e32 v45, 0xffff0000, v82
	v_lshlrev_b32_e32 v82, 16, v83
	v_and_b32_e32 v83, 0xffff0000, v83
	v_pk_add_f32 v[66:67], v[66:67], v[44:45]
	v_pk_add_f32 v[68:69], v[68:69], v[82:83]
	v_cvt_pk_bf16_f32 v66, v66, v67
	v_cvt_pk_bf16_f32 v67, v68, v69
	global_store_dwordx2 v[84:85], v[66:67], off
	ds_read_b128 v[66:69], v224
	v_mfma_f32_16x16x32_bf16 v[44:47], v[70:73], v[32:35], 0
	v_mfma_f32_16x16x32_bf16 v[32:35], v[48:51], v[32:35], 0
	v_mfma_f32_16x16x32_bf16 v[48:51], v[78:81], v[36:39], v[32:35]
	v_lshl_add_u64 v[36:37], s[4:5], 0, v[112:113]
	v_cvt_pk_bf16_f32 v38, v74, v75
	ds_read_b128 v[78:81], v225
	v_cvt_pk_bf16_f32 v39, v76, v77
	global_store_dwordx2 v[36:37], v[38:39], off
	ds_read_b128 v[36:39], v183 offset:53568
	v_mfma_f32_16x16x32_bf16 v[32:35], v[70:73], v[58:61], 0
	s_waitcnt lgkmcnt(0)
	v_mfma_f32_16x16x32_bf16 v[58:61], v[66:69], v[62:65], 0
	v_add_f32_e64 v66, v2, v28
	v_add_f32_e64 v67, v3, v29
	ds_read_b64 v[28:29], v235 offset:51200
	ds_read_b128 v[62:65], v184 offset:64
	v_pk_mul_f32 v[66:67], v[56:57], v[66:67] op_sel_hi:[0,1]
	v_mfma_f32_16x16x32_bf16 v[52:55], v[78:81], v[52:55], v[58:61]
	ds_read_b64 v[68:69], v215 offset:51200
	s_nop 1
	ds_read_b128 v[58:61], v223 offset:64
	s_waitcnt lgkmcnt(0)
	v_pk_mul_f32 v[40:41], v[40:41], v[28:29]
	v_pk_add_f32 v[28:29], v[104:105], v[30:31]
	v_mfma_f32_16x16x32_bf16 v[44:47], v[36:39], v[24:27], v[44:47]
	v_mul_f32_e64 v70, v56, v28
	v_mul_f32_e64 v71, v56, v29
	ds_read_b128 v[28:31], v224 offset:64
	v_pk_mul_f32 v[42:43], v[42:43], v[68:69]
	v_mfma_f32_16x16x32_bf16 v[24:27], v[62:65], v[24:27], v[48:51]
	v_mfma_f32_16x16x32_bf16 v[20:23], v[58:61], v[20:23], v[24:27]
	s_nop 1
	v_lshl_add_u64 v[48:49], s[34:35], 0, v[110:111]
	v_cvt_pk_bf16_f32 v50, v66, v67
	v_cvt_pk_bf16_f32 v51, v70, v71
	s_nop 1
	ds_read_b128 v[24:27], v225 offset:64
	s_waitcnt lgkmcnt(0)
	v_mfma_f32_16x16x32_bf16 v[12:15], v[28:31], v[12:15], v[52:55]
	ds_read_b64 v[28:29], v221
	global_store_dwordx2 v[48:49], v[50:51], off
	v_mfma_f32_16x16x32_bf16 v[8:11], v[24:27], v[8:11], v[12:15]
	s_waitcnt lgkmcnt(0)
	s_nop 3
	v_lshlrev_b32_e32 v14, 16, v28
	v_and_b32_e32 v15, 0xffff0000, v28
	v_lshlrev_b32_e32 v24, 16, v29
	v_and_b32_e32 v25, 0xffff0000, v29
	v_pk_add_f32 v[14:15], v[44:45], v[14:15]
	v_pk_add_f32 v[24:25], v[46:47], v[24:25]
	v_mfma_f32_16x16x32_bf16 v[16:19], v[36:39], v[16:19], v[32:35]
	v_lshl_add_u64 v[12:13], s[0:1], 0, v[114:115]
	v_cvt_pk_bf16_f32 v14, v14, v15
	v_cvt_pk_bf16_f32 v15, v24, v25
	v_lshl_add_u64 v[32:33], vcc, 0, v[112:113]
	v_cvt_pk_bf16_f32 v34, v40, v41
	v_cvt_pk_bf16_f32 v35, v42, v43
	global_store_dwordx2 v[32:33], v[34:35], off
	global_store_dwordx2 v[12:13], v[14:15], off
	v_lshl_add_u64 v[12:13], s[4:5], 0, v[116:117]
	v_cvt_pk_bf16_f32 v14, v20, v21
	v_cvt_pk_bf16_f32 v15, v22, v23
	ds_read_b64 v[20:21], v236 offset:51200
	global_store_dwordx2 v[12:13], v[14:15], off
	ds_read_b64 v[14:15], v222 offset:51200
	v_pk_add_f32 v[12:13], v[106:107], v[16:17]
	v_pk_add_f32 v[16:17], v[108:109], v[18:19]
	v_pk_mul_f32 v[12:13], v[56:57], v[12:13] op_sel_hi:[0,1]
	v_pk_mul_f32 v[16:17], v[56:57], v[16:17] op_sel_hi:[0,1]
	s_waitcnt lgkmcnt(0)
	v_pk_mul_f32 v[8:9], v[8:9], v[20:21]
	v_pk_mul_f32 v[10:11], v[10:11], v[14:15]
	v_lshl_add_u64 v[14:15], s[34:35], 0, v[114:115]
	v_cvt_pk_bf16_f32 v12, v12, v13
	v_cvt_pk_bf16_f32 v13, v16, v17
	global_store_dwordx2 v[14:15], v[12:13], off
	v_lshl_add_u64 v[12:13], vcc, 0, v[116:117]
	v_cvt_pk_bf16_f32 v8, v8, v9
	v_cvt_pk_bf16_f32 v9, v10, v11
	s_and_b64 vcc, exec, s[8:9]
	s_mov_b32 s34, s40
	global_store_dwordx2 v[12:13], v[8:9], off
	s_cbranch_vccnz .LBB0_544

.LBB0_544:
	s_setprio 0
	v_readlane_b32 s96, v254, 0
	v_readlane_b32 s86, v253, 60
	v_readlane_b32 s6, v254, 2
	s_mov_b64 s[0:1], 0
	s_movk_i32 s93, 0x7f
	s_movk_i32 s78, 0xfff
	v_readlane_b32 s97, v254, 1
	s_mov_b64 s[52:53], 0
	v_readlane_b32 s68, v253, 56
	v_readlane_b32 s69, v253, 58
	v_readlane_b32 s87, v253, 61
	v_readlane_b32 s70, v253, 62
	v_readlane_b32 s7, v254, 3
